# in-projection epilogue: row addresses from the first row address plus a running scalar byte delta (s_add_u32/s_addc_u32), no per-row 64-bit multiply chains
# speedup vs baseline: 1.0038x; 1.0038x over previous
; __device__ __forceinline__ unsigned cvt_pk(float lo, float hi) { unsigned r; asm volatile("v_cvt_pk_bf16_f32 %0, %1, %2" : "=v"(r) : "v"(lo), "v"(hi)); return r; }
;     __device__ __forceinline__ void operator()(const f32x4 (&acc)[2][2][4][2], const Unit& u, int wr, int wc, int fr, int fq) const {
;     ...
;         const int row0 = u.pm * BM + wr * 64 + fr, col0 = colt + wc * 32 + 8 * fq;
; #pragma unroll
;         for (int ai = 0; ai < 2; ++ai)
; #pragma unroll
;             for (int m = 0; m < 4; ++m) { const int row = row0 + ai * HALF + m * 16; const float rs = sc; bf16_t* rowp = base + (size_t)row * ldc + col0;
; #pragma unroll
;                 for (int bj = 0; bj < 2; ++bj) { const f32x4 v0 = acc[ai][bj][m][0] * rs, v1 = acc[ai][bj][m][1] * rs;
;                     u32x4 w; w.x = cvt_pk(v0[0], v0[1]); w.y = cvt_pk(v0[2], v0[3]); w.z = cvt_pk(v1[0], v1[1]); w.w = cvt_pk(v1[2], v1[3]);
;                     if (pn == 4 || pn == 5) *(u32x4*)((pn == 4 ? KB : VB) + ((size_t)bj * 40960 + row) * 128 + wc * 32 + 8 * fq) = w;
;                     else if (pn >= 18) __builtin_nontemporal_store(w, (u32x4*)(rowp + bj * HALF));
;                     else *(u32x4*)(rowp + bj * HALF) = w; } }
.LBB0_213:
	v_lshl_add_u32 v154, s2, 8, v158
	s_and_b32 s2, s3, -2
	v_add_u32_e32 v152, s21, v160
	s_cmp_lg_u32 s2, 4
	v_ashrrev_i32_e32 v155, 31, v154
	v_ashrrev_i32_e32 v153, 31, v152
	s_cselect_b64 s[34:35], -1, 0
	s_cmp_eq_u32 s3, 4
	v_mul_lo_u32 v140, s30, v155
	v_mul_lo_u32 v151, s31, v154
	v_mad_u64_u32 v[156:157], s[2:3], s30, v154, 0
	v_lshl_add_u64 v[152:153], v[152:153], 1, s[28:29]
	v_add3_u32 v157, v157, v140, v151
	s_cselect_b64 s[28:29], -1, 0
	v_lshl_add_u64 v[156:157], v[156:157], 1, v[152:153]
	s_lshl_b64 s[90:91], s[30:31], 5
	s_mov_b64 s[88:89], 0
	v_pk_mul_f32 v[166:167], v[124:125], v[150:151] op_sel_hi:[1,0]
	v_pk_mul_f32 v[124:125], v[122:123], v[150:151] op_sel_hi:[1,0]
	s_mov_b64 s[2:3], -1
	s_and_b64 vcc, exec, s[34:35]
	v_pk_mul_f32 v[128:129], v[128:129], v[150:151] op_sel_hi:[1,0]
	v_pk_mul_f32 v[126:127], v[126:127], v[150:151] op_sel_hi:[1,0]
	s_nop 0
	v_cvt_pk_bf16_f32 v122, v126, v127
	v_cvt_pk_bf16_f32 v123, v128, v129
	v_cvt_pk_bf16_f32 v124, v124, v125
	v_cvt_pk_bf16_f32 v125, v166, v167
	s_cbranch_vccz .LBB0_215
	global_store_dwordx4 v[156:157], v[122:125], off
	s_mov_b64 s[2:3], 0

; __device__ __forceinline__ unsigned cvt_pk(float lo, float hi) { unsigned r; asm volatile("v_cvt_pk_bf16_f32 %0, %1, %2" : "=v"(r) : "v"(lo), "v"(hi)); return r; }
;     __device__ __forceinline__ void operator()(const f32x4 (&acc)[2][2][4][2], const Unit& u, int wr, int wc, int fr, int fq) const {
;     ...
;         const int row0 = u.pm * BM + wr * 64 + fr, col0 = colt + wc * 32 + 8 * fq;
; #pragma unroll
;         for (int ai = 0; ai < 2; ++ai)
; #pragma unroll
;             for (int m = 0; m < 4; ++m) { const int row = row0 + ai * HALF + m * 16; const float rs = sc; bf16_t* rowp = base + (size_t)row * ldc + col0;
; #pragma unroll
;                 for (int bj = 0; bj < 2; ++bj) { const f32x4 v0 = acc[ai][bj][m][0] * rs, v1 = acc[ai][bj][m][1] * rs;
;                     u32x4 w; w.x = cvt_pk(v0[0], v0[1]); w.y = cvt_pk(v0[2], v0[3]); w.z = cvt_pk(v1[0], v1[1]); w.w = cvt_pk(v1[2], v1[3]);
;                     if (pn == 4 || pn == 5) *(u32x4*)((pn == 4 ? KB : VB) + ((size_t)bj * 40960 + row) * 128 + wc * 32 + 8 * fq) = w;
;                     else if (pn >= 18) __builtin_nontemporal_store(w, (u32x4*)(rowp + bj * HALF));
;                     else *(u32x4*)(rowp + bj * HALF) = w; } }
.LBB0_221:
	s_nop 1
	v_or_b32_e32 v116, 16, v154
	v_ashrrev_i32_e32 v117, 31, v116
	v_mov_b32_e32 v118, v150
	v_mov_b32_e32 v119, v150
	s_add_u32 s88, s88, s90
	s_addc_u32 s89, s89, s91
	v_lshl_add_u64 v[114:115], v[156:157], 0, s[88:89]
	v_pk_mul_f32 v[112:113], v[112:113], v[118:119]
	v_pk_mul_f32 v[118:119], v[108:109], v[118:119]
	v_pk_mul_f32 v[108:109], v[106:107], v[150:151]
	s_and_b64 vcc, exec, s[2:3]
	s_mov_b64 s[34:35], -1
	v_pk_mul_f32 v[110:111], v[110:111], v[150:151]
	s_nop 0
	v_cvt_pk_bf16_f32 v106, v110, v111
	v_cvt_pk_bf16_f32 v107, v112, v113
	v_cvt_pk_bf16_f32 v108, v108, v109
	v_cvt_pk_bf16_f32 v109, v118, v119
	s_cbranch_vccnz .LBB0_223
	s_mov_b64 s[34:35], 0
	global_store_dwordx4 v[114:115], v[106:109], off

; __device__ __forceinline__ unsigned cvt_pk(float lo, float hi) { unsigned r; asm volatile("v_cvt_pk_bf16_f32 %0, %1, %2" : "=v"(r) : "v"(lo), "v"(hi)); return r; }
;     __device__ __forceinline__ void operator()(const f32x4 (&acc)[2][2][4][2], const Unit& u, int wr, int wc, int fr, int fq) const {
;     ...
;         const int row0 = u.pm * BM + wr * 64 + fr, col0 = colt + wc * 32 + 8 * fq;
; #pragma unroll
;         for (int ai = 0; ai < 2; ++ai)
; #pragma unroll
;             for (int m = 0; m < 4; ++m) { const int row = row0 + ai * HALF + m * 16; const float rs = sc; bf16_t* rowp = base + (size_t)row * ldc + col0;
; #pragma unroll
;                 for (int bj = 0; bj < 2; ++bj) { const f32x4 v0 = acc[ai][bj][m][0] * rs, v1 = acc[ai][bj][m][1] * rs;
;                     u32x4 w; w.x = cvt_pk(v0[0], v0[1]); w.y = cvt_pk(v0[2], v0[3]); w.z = cvt_pk(v1[0], v1[1]); w.w = cvt_pk(v1[2], v1[3]);
;                     if (pn == 4 || pn == 5) *(u32x4*)((pn == 4 ? KB : VB) + ((size_t)bj * 40960 + row) * 128 + wc * 32 + 8 * fq) = w;
;                     else if (pn >= 18) __builtin_nontemporal_store(w, (u32x4*)(rowp + bj * HALF));
;                     else *(u32x4*)(rowp + bj * HALF) = w; } }
.LBB0_229:
	s_nop 1
	v_or_b32_e32 v100, 32, v154
	v_ashrrev_i32_e32 v101, 31, v100
	v_mov_b32_e32 v102, v150
	v_mov_b32_e32 v103, v150
	s_add_u32 s88, s88, s90
	s_addc_u32 s89, s89, s91
	v_lshl_add_u64 v[98:99], v[156:157], 0, s[88:89]
	v_pk_mul_f32 v[96:97], v[96:97], v[102:103]
	v_pk_mul_f32 v[102:103], v[92:93], v[102:103]
	v_pk_mul_f32 v[92:93], v[90:91], v[150:151]
	s_and_b64 vcc, exec, s[2:3]
	s_mov_b64 s[34:35], -1
	v_pk_mul_f32 v[94:95], v[94:95], v[150:151]
	s_nop 0
	v_cvt_pk_bf16_f32 v90, v94, v95
	v_cvt_pk_bf16_f32 v91, v96, v97
	v_cvt_pk_bf16_f32 v92, v92, v93
	v_cvt_pk_bf16_f32 v93, v102, v103
	s_cbranch_vccnz .LBB0_231
	s_mov_b64 s[34:35], 0
	global_store_dwordx4 v[98:99], v[90:93], off

; __device__ __forceinline__ unsigned cvt_pk(float lo, float hi) { unsigned r; asm volatile("v_cvt_pk_bf16_f32 %0, %1, %2" : "=v"(r) : "v"(lo), "v"(hi)); return r; }
;     __device__ __forceinline__ void operator()(const f32x4 (&acc)[2][2][4][2], const Unit& u, int wr, int wc, int fr, int fq) const {
;     ...
;         const int row0 = u.pm * BM + wr * 64 + fr, col0 = colt + wc * 32 + 8 * fq;
; #pragma unroll
;         for (int ai = 0; ai < 2; ++ai)
; #pragma unroll
;             for (int m = 0; m < 4; ++m) { const int row = row0 + ai * HALF + m * 16; const float rs = sc; bf16_t* rowp = base + (size_t)row * ldc + col0;
; #pragma unroll
;                 for (int bj = 0; bj < 2; ++bj) { const f32x4 v0 = acc[ai][bj][m][0] * rs, v1 = acc[ai][bj][m][1] * rs;
;                     u32x4 w; w.x = cvt_pk(v0[0], v0[1]); w.y = cvt_pk(v0[2], v0[3]); w.z = cvt_pk(v1[0], v1[1]); w.w = cvt_pk(v1[2], v1[3]);
;                     if (pn == 4 || pn == 5) *(u32x4*)((pn == 4 ? KB : VB) + ((size_t)bj * 40960 + row) * 128 + wc * 32 + 8 * fq) = w;
;                     else if (pn >= 18) __builtin_nontemporal_store(w, (u32x4*)(rowp + bj * HALF));
;                     else *(u32x4*)(rowp + bj * HALF) = w; } }
.LBB0_237:
	s_nop 1
	v_or_b32_e32 v84, 48, v154
	v_ashrrev_i32_e32 v85, 31, v84
	v_mov_b32_e32 v86, v150
	v_mov_b32_e32 v87, v150
	s_add_u32 s88, s88, s90
	s_addc_u32 s89, s89, s91
	v_lshl_add_u64 v[82:83], v[156:157], 0, s[88:89]
	v_pk_mul_f32 v[80:81], v[80:81], v[86:87]
	v_pk_mul_f32 v[86:87], v[76:77], v[86:87]
	v_pk_mul_f32 v[76:77], v[74:75], v[150:151]
	s_and_b64 vcc, exec, s[2:3]
	s_mov_b64 s[34:35], -1
	v_pk_mul_f32 v[78:79], v[78:79], v[150:151]
	s_nop 0
	v_cvt_pk_bf16_f32 v74, v78, v79
	v_cvt_pk_bf16_f32 v75, v80, v81
	v_cvt_pk_bf16_f32 v76, v76, v77
	v_cvt_pk_bf16_f32 v77, v86, v87
	s_cbranch_vccnz .LBB0_239
	s_mov_b64 s[34:35], 0
	global_store_dwordx4 v[82:83], v[74:77], off

; __device__ __forceinline__ unsigned cvt_pk(float lo, float hi) { unsigned r; asm volatile("v_cvt_pk_bf16_f32 %0, %1, %2" : "=v"(r) : "v"(lo), "v"(hi)); return r; }
;     __device__ __forceinline__ void operator()(const f32x4 (&acc)[2][2][4][2], const Unit& u, int wr, int wc, int fr, int fq) const {
;     ...
;         const int row0 = u.pm * BM + wr * 64 + fr, col0 = colt + wc * 32 + 8 * fq;
; #pragma unroll
;         for (int ai = 0; ai < 2; ++ai)
; #pragma unroll
;             for (int m = 0; m < 4; ++m) { const int row = row0 + ai * HALF + m * 16; const float rs = sc; bf16_t* rowp = base + (size_t)row * ldc + col0;
; #pragma unroll
;                 for (int bj = 0; bj < 2; ++bj) { const f32x4 v0 = acc[ai][bj][m][0] * rs, v1 = acc[ai][bj][m][1] * rs;
;                     u32x4 w; w.x = cvt_pk(v0[0], v0[1]); w.y = cvt_pk(v0[2], v0[3]); w.z = cvt_pk(v1[0], v1[1]); w.w = cvt_pk(v1[2], v1[3]);
;                     if (pn == 4 || pn == 5) *(u32x4*)((pn == 4 ? KB : VB) + ((size_t)bj * 40960 + row) * 128 + wc * 32 + 8 * fq) = w;
;                     else if (pn >= 18) __builtin_nontemporal_store(w, (u32x4*)(rowp + bj * HALF));
;                     else *(u32x4*)(rowp + bj * HALF) = w; } }
.LBB0_245:
	s_nop 1
	v_add_u32_e32 v68, 0x80, v154
	v_ashrrev_i32_e32 v69, 31, v68
	v_mov_b32_e32 v70, v150
	v_mov_b32_e32 v71, v150
	s_lshl_b64 s[88:89], s[90:91], 3
	v_lshl_add_u64 v[66:67], v[156:157], 0, s[88:89]
	v_pk_mul_f32 v[64:65], v[64:65], v[70:71]
	v_pk_mul_f32 v[70:71], v[60:61], v[70:71]
	v_pk_mul_f32 v[60:61], v[58:59], v[150:151]
	s_and_b64 vcc, exec, s[2:3]
	s_mov_b64 s[34:35], -1
	v_pk_mul_f32 v[62:63], v[62:63], v[150:151]
	s_nop 0
	v_cvt_pk_bf16_f32 v58, v62, v63
	v_cvt_pk_bf16_f32 v59, v64, v65
	v_cvt_pk_bf16_f32 v60, v60, v61
	v_cvt_pk_bf16_f32 v61, v70, v71
	s_cbranch_vccnz .LBB0_247
	s_mov_b64 s[34:35], 0
	global_store_dwordx4 v[66:67], v[58:61], off

; __device__ __forceinline__ unsigned cvt_pk(float lo, float hi) { unsigned r; asm volatile("v_cvt_pk_bf16_f32 %0, %1, %2" : "=v"(r) : "v"(lo), "v"(hi)); return r; }
;     __device__ __forceinline__ void operator()(const f32x4 (&acc)[2][2][4][2], const Unit& u, int wr, int wc, int fr, int fq) const {
;     ...
;         const int row0 = u.pm * BM + wr * 64 + fr, col0 = colt + wc * 32 + 8 * fq;
; #pragma unroll
;         for (int ai = 0; ai < 2; ++ai)
; #pragma unroll
;             for (int m = 0; m < 4; ++m) { const int row = row0 + ai * HALF + m * 16; const float rs = sc; bf16_t* rowp = base + (size_t)row * ldc + col0;
; #pragma unroll
;                 for (int bj = 0; bj < 2; ++bj) { const f32x4 v0 = acc[ai][bj][m][0] * rs, v1 = acc[ai][bj][m][1] * rs;
;                     u32x4 w; w.x = cvt_pk(v0[0], v0[1]); w.y = cvt_pk(v0[2], v0[3]); w.z = cvt_pk(v1[0], v1[1]); w.w = cvt_pk(v1[2], v1[3]);
;                     if (pn == 4 || pn == 5) *(u32x4*)((pn == 4 ? KB : VB) + ((size_t)bj * 40960 + row) * 128 + wc * 32 + 8 * fq) = w;
;                     else if (pn >= 18) __builtin_nontemporal_store(w, (u32x4*)(rowp + bj * HALF));
;                     else *(u32x4*)(rowp + bj * HALF) = w; } }
.LBB0_253:
	s_nop 1
	v_add_u32_e32 v52, 0x90, v154
	v_ashrrev_i32_e32 v53, 31, v52
	v_mov_b32_e32 v54, v150
	v_mov_b32_e32 v55, v150
	s_add_u32 s88, s88, s90
	s_addc_u32 s89, s89, s91
	v_lshl_add_u64 v[50:51], v[156:157], 0, s[88:89]
	v_pk_mul_f32 v[48:49], v[48:49], v[54:55]
	v_pk_mul_f32 v[54:55], v[44:45], v[54:55]
	v_pk_mul_f32 v[44:45], v[42:43], v[150:151]
	s_and_b64 vcc, exec, s[2:3]
	s_mov_b64 s[34:35], -1
	v_pk_mul_f32 v[46:47], v[46:47], v[150:151]
	s_nop 0
	v_cvt_pk_bf16_f32 v42, v46, v47
	v_cvt_pk_bf16_f32 v43, v48, v49
	v_cvt_pk_bf16_f32 v44, v44, v45
	v_cvt_pk_bf16_f32 v45, v54, v55
	s_cbranch_vccnz .LBB0_255
	s_mov_b64 s[34:35], 0
	global_store_dwordx4 v[50:51], v[42:45], off

; __device__ __forceinline__ unsigned cvt_pk(float lo, float hi) { unsigned r; asm volatile("v_cvt_pk_bf16_f32 %0, %1, %2" : "=v"(r) : "v"(lo), "v"(hi)); return r; }
;     __device__ __forceinline__ void operator()(const f32x4 (&acc)[2][2][4][2], const Unit& u, int wr, int wc, int fr, int fq) const {
;     ...
;         const int row0 = u.pm * BM + wr * 64 + fr, col0 = colt + wc * 32 + 8 * fq;
; #pragma unroll
;         for (int ai = 0; ai < 2; ++ai)
; #pragma unroll
;             for (int m = 0; m < 4; ++m) { const int row = row0 + ai * HALF + m * 16; const float rs = sc; bf16_t* rowp = base + (size_t)row * ldc + col0;
; #pragma unroll
;                 for (int bj = 0; bj < 2; ++bj) { const f32x4 v0 = acc[ai][bj][m][0] * rs, v1 = acc[ai][bj][m][1] * rs;
;                     u32x4 w; w.x = cvt_pk(v0[0], v0[1]); w.y = cvt_pk(v0[2], v0[3]); w.z = cvt_pk(v1[0], v1[1]); w.w = cvt_pk(v1[2], v1[3]);
;                     if (pn == 4 || pn == 5) *(u32x4*)((pn == 4 ? KB : VB) + ((size_t)bj * 40960 + row) * 128 + wc * 32 + 8 * fq) = w;
;                     else if (pn >= 18) __builtin_nontemporal_store(w, (u32x4*)(rowp + bj * HALF));
;                     else *(u32x4*)(rowp + bj * HALF) = w; } }
.LBB0_261:
	s_nop 1
	v_add_u32_e32 v36, 0xa0, v154
	v_ashrrev_i32_e32 v37, 31, v36
	v_mov_b32_e32 v38, v150
	v_mov_b32_e32 v39, v150
	s_add_u32 s88, s88, s90
	s_addc_u32 s89, s89, s91
	v_lshl_add_u64 v[34:35], v[156:157], 0, s[88:89]
	v_pk_mul_f32 v[32:33], v[32:33], v[38:39]
	v_pk_mul_f32 v[38:39], v[28:29], v[38:39]
	v_pk_mul_f32 v[28:29], v[26:27], v[150:151]
	s_and_b64 vcc, exec, s[2:3]
	s_mov_b64 s[34:35], -1
	v_pk_mul_f32 v[30:31], v[30:31], v[150:151]
	s_nop 0
	v_cvt_pk_bf16_f32 v26, v30, v31
	v_cvt_pk_bf16_f32 v27, v32, v33
	v_cvt_pk_bf16_f32 v28, v28, v29
	v_cvt_pk_bf16_f32 v29, v38, v39
	s_cbranch_vccnz .LBB0_263
	s_mov_b64 s[34:35], 0
	global_store_dwordx4 v[34:35], v[26:29], off

; __device__ __forceinline__ unsigned cvt_pk(float lo, float hi) { unsigned r; asm volatile("v_cvt_pk_bf16_f32 %0, %1, %2" : "=v"(r) : "v"(lo), "v"(hi)); return r; }
;     __device__ __forceinline__ void operator()(const f32x4 (&acc)[2][2][4][2], const Unit& u, int wr, int wc, int fr, int fq) const {
;     ...
;         const int row0 = u.pm * BM + wr * 64 + fr, col0 = colt + wc * 32 + 8 * fq;
; #pragma unroll
;         for (int ai = 0; ai < 2; ++ai)
; #pragma unroll
;             for (int m = 0; m < 4; ++m) { const int row = row0 + ai * HALF + m * 16; const float rs = sc; bf16_t* rowp = base + (size_t)row * ldc + col0;
; #pragma unroll
;                 for (int bj = 0; bj < 2; ++bj) { const f32x4 v0 = acc[ai][bj][m][0] * rs, v1 = acc[ai][bj][m][1] * rs;
;                     u32x4 w; w.x = cvt_pk(v0[0], v0[1]); w.y = cvt_pk(v0[2], v0[3]); w.z = cvt_pk(v1[0], v1[1]); w.w = cvt_pk(v1[2], v1[3]);
;                     if (pn == 4 || pn == 5) *(u32x4*)((pn == 4 ? KB : VB) + ((size_t)bj * 40960 + row) * 128 + wc * 32 + 8 * fq) = w;
;                     else if (pn >= 18) __builtin_nontemporal_store(w, (u32x4*)(rowp + bj * HALF));
;                     else *(u32x4*)(rowp + bj * HALF) = w; } }
.LBB0_269:
	s_nop 1
	v_add_u32_e32 v20, 0xb0, v154
	v_ashrrev_i32_e32 v21, 31, v20
	v_mov_b32_e32 v22, v150
	v_mov_b32_e32 v23, v150
	s_add_u32 s88, s88, s90
	s_addc_u32 s89, s89, s91
	v_lshl_add_u64 v[18:19], v[156:157], 0, s[88:89]
	v_pk_mul_f32 v[16:17], v[16:17], v[22:23]
	v_pk_mul_f32 v[22:23], v[12:13], v[22:23]
	v_pk_mul_f32 v[12:13], v[10:11], v[150:151]
	s_and_b64 vcc, exec, s[2:3]
	s_mov_b64 s[30:31], -1
	v_pk_mul_f32 v[14:15], v[14:15], v[150:151]
	s_nop 0
	v_cvt_pk_bf16_f32 v10, v14, v15
	v_cvt_pk_bf16_f32 v11, v16, v17
	v_cvt_pk_bf16_f32 v12, v12, v13
	v_cvt_pk_bf16_f32 v13, v22, v23
	s_cbranch_vccnz .LBB0_271
	s_mov_b64 s[30:31], 0
	global_store_dwordx4 v[18:19], v[10:13], off

; __device__ __forceinline__ unsigned cvt_pk(float lo, float hi) { unsigned r; asm volatile("v_cvt_pk_bf16_f32 %0, %1, %2" : "=v"(r) : "v"(lo), "v"(hi)); return r; }
;     __device__ __forceinline__ void operator()(const f32x4 (&acc)[2][2][4][2], const Unit& u, int wr, int wc, int fr, int fq) const {
;     ...
;         const int row0 = u.pm * BM + wr * 64 + fr, col0 = colt + wc * 32 + 8 * fq;
; #pragma unroll
;         for (int ai = 0; ai < 2; ++ai)
; #pragma unroll
;             for (int m = 0; m < 4; ++m) { const int row = row0 + ai * HALF + m * 16; const float rs = sc; bf16_t* rowp = base + (size_t)row * ldc + col0;
; #pragma unroll
;                 for (int bj = 0; bj < 2; ++bj) { const f32x4 v0 = acc[ai][bj][m][0] * rs, v1 = acc[ai][bj][m][1] * rs;
;                     u32x4 w; w.x = cvt_pk(v0[0], v0[1]); w.y = cvt_pk(v0[2], v0[3]); w.z = cvt_pk(v1[0], v1[1]); w.w = cvt_pk(v1[2], v1[3]);
;                     if (pn == 4 || pn == 5) *(u32x4*)((pn == 4 ? KB : VB) + ((size_t)bj * 40960 + row) * 128 + wc * 32 + 8 * fq) = w;
;                     else if (pn >= 18) __builtin_nontemporal_store(w, (u32x4*)(rowp + bj * HALF));
;                     else *(u32x4*)(rowp + bj * HALF) = w; } }
.LBB0_775:
	v_lshl_add_u32 v156, s2, 8, v147
	s_and_b32 s2, s3, -2
	v_add_u32_e32 v154, s21, v162
	s_cmp_lg_u32 s2, 4
	v_ashrrev_i32_e32 v157, 31, v156
	v_ashrrev_i32_e32 v155, 31, v154
	s_cselect_b64 s[34:35], -1, 0
	s_cmp_eq_u32 s3, 4
	v_mul_lo_u32 v140, s30, v157
	v_mul_lo_u32 v153, s31, v156
	v_mad_u64_u32 v[158:159], s[2:3], s30, v156, 0
	v_lshl_add_u64 v[154:155], v[154:155], 1, s[28:29]
	v_add3_u32 v159, v159, v140, v153
	s_cselect_b64 s[28:29], -1, 0
	v_lshl_add_u64 v[158:159], v[158:159], 1, v[154:155]
	s_lshl_b64 s[90:91], s[30:31], 5
	s_mov_b64 s[88:89], 0
	v_pk_mul_f32 v[170:171], v[124:125], v[152:153] op_sel_hi:[1,0]
	v_pk_mul_f32 v[124:125], v[122:123], v[152:153] op_sel_hi:[1,0]
	s_mov_b64 s[2:3], -1
	s_and_b64 vcc, exec, s[34:35]
	v_pk_mul_f32 v[128:129], v[128:129], v[152:153] op_sel_hi:[1,0]
	v_pk_mul_f32 v[126:127], v[126:127], v[152:153] op_sel_hi:[1,0]
	s_nop 0
	v_cvt_pk_bf16_f32 v122, v126, v127
	v_cvt_pk_bf16_f32 v123, v128, v129
	v_cvt_pk_bf16_f32 v124, v124, v125
	v_cvt_pk_bf16_f32 v125, v170, v171
	s_cbranch_vccz .LBB0_777
	global_store_dwordx4 v[158:159], v[122:125], off
	s_mov_b64 s[2:3], 0

; __device__ __forceinline__ unsigned cvt_pk(float lo, float hi) { unsigned r; asm volatile("v_cvt_pk_bf16_f32 %0, %1, %2" : "=v"(r) : "v"(lo), "v"(hi)); return r; }
;     __device__ __forceinline__ void operator()(const f32x4 (&acc)[2][2][4][2], const Unit& u, int wr, int wc, int fr, int fq) const {
;     ...
;         const int row0 = u.pm * BM + wr * 64 + fr, col0 = colt + wc * 32 + 8 * fq;
; #pragma unroll
;         for (int ai = 0; ai < 2; ++ai)
; #pragma unroll
;             for (int m = 0; m < 4; ++m) { const int row = row0 + ai * HALF + m * 16; const float rs = sc; bf16_t* rowp = base + (size_t)row * ldc + col0;
; #pragma unroll
;                 for (int bj = 0; bj < 2; ++bj) { const f32x4 v0 = acc[ai][bj][m][0] * rs, v1 = acc[ai][bj][m][1] * rs;
;                     u32x4 w; w.x = cvt_pk(v0[0], v0[1]); w.y = cvt_pk(v0[2], v0[3]); w.z = cvt_pk(v1[0], v1[1]); w.w = cvt_pk(v1[2], v1[3]);
;                     if (pn == 4 || pn == 5) *(u32x4*)((pn == 4 ? KB : VB) + ((size_t)bj * 40960 + row) * 128 + wc * 32 + 8 * fq) = w;
;                     else if (pn >= 18) __builtin_nontemporal_store(w, (u32x4*)(rowp + bj * HALF));
;                     else *(u32x4*)(rowp + bj * HALF) = w; } }
.LBB0_783:
	s_nop 1
	v_or_b32_e32 v116, 16, v156
	v_ashrrev_i32_e32 v117, 31, v116
	v_mov_b32_e32 v118, v152
	v_mov_b32_e32 v119, v152
	s_add_u32 s88, s88, s90
	s_addc_u32 s89, s89, s91
	v_lshl_add_u64 v[114:115], v[158:159], 0, s[88:89]
	v_pk_mul_f32 v[112:113], v[112:113], v[118:119]
	v_pk_mul_f32 v[118:119], v[108:109], v[118:119]
	v_pk_mul_f32 v[108:109], v[106:107], v[152:153]
	s_and_b64 vcc, exec, s[2:3]
	s_mov_b64 s[34:35], -1
	v_pk_mul_f32 v[110:111], v[110:111], v[152:153]
	s_nop 0
	v_cvt_pk_bf16_f32 v106, v110, v111
	v_cvt_pk_bf16_f32 v107, v112, v113
	v_cvt_pk_bf16_f32 v108, v108, v109
	v_cvt_pk_bf16_f32 v109, v118, v119
	s_cbranch_vccnz .LBB0_785
	s_mov_b64 s[34:35], 0
	global_store_dwordx4 v[114:115], v[106:109], off

; __device__ __forceinline__ unsigned cvt_pk(float lo, float hi) { unsigned r; asm volatile("v_cvt_pk_bf16_f32 %0, %1, %2" : "=v"(r) : "v"(lo), "v"(hi)); return r; }
;     __device__ __forceinline__ void operator()(const f32x4 (&acc)[2][2][4][2], const Unit& u, int wr, int wc, int fr, int fq) const {
;     ...
;         const int row0 = u.pm * BM + wr * 64 + fr, col0 = colt + wc * 32 + 8 * fq;
; #pragma unroll
;         for (int ai = 0; ai < 2; ++ai)
; #pragma unroll
;             for (int m = 0; m < 4; ++m) { const int row = row0 + ai * HALF + m * 16; const float rs = sc; bf16_t* rowp = base + (size_t)row * ldc + col0;
; #pragma unroll
;                 for (int bj = 0; bj < 2; ++bj) { const f32x4 v0 = acc[ai][bj][m][0] * rs, v1 = acc[ai][bj][m][1] * rs;
;                     u32x4 w; w.x = cvt_pk(v0[0], v0[1]); w.y = cvt_pk(v0[2], v0[3]); w.z = cvt_pk(v1[0], v1[1]); w.w = cvt_pk(v1[2], v1[3]);
;                     if (pn == 4 || pn == 5) *(u32x4*)((pn == 4 ? KB : VB) + ((size_t)bj * 40960 + row) * 128 + wc * 32 + 8 * fq) = w;
;                     else if (pn >= 18) __builtin_nontemporal_store(w, (u32x4*)(rowp + bj * HALF));
;                     else *(u32x4*)(rowp + bj * HALF) = w; } }
.LBB0_791:
	s_nop 1
	v_or_b32_e32 v100, 32, v156
	v_ashrrev_i32_e32 v101, 31, v100
	v_mov_b32_e32 v102, v152
	v_mov_b32_e32 v103, v152
	s_add_u32 s88, s88, s90
	s_addc_u32 s89, s89, s91
	v_lshl_add_u64 v[98:99], v[158:159], 0, s[88:89]
	v_pk_mul_f32 v[96:97], v[96:97], v[102:103]
	v_pk_mul_f32 v[102:103], v[92:93], v[102:103]
	v_pk_mul_f32 v[92:93], v[90:91], v[152:153]
	s_and_b64 vcc, exec, s[2:3]
	s_mov_b64 s[34:35], -1
	v_pk_mul_f32 v[94:95], v[94:95], v[152:153]
	s_nop 0
	v_cvt_pk_bf16_f32 v90, v94, v95
	v_cvt_pk_bf16_f32 v91, v96, v97
	v_cvt_pk_bf16_f32 v92, v92, v93
	v_cvt_pk_bf16_f32 v93, v102, v103
	s_cbranch_vccnz .LBB0_793
	s_mov_b64 s[34:35], 0
	global_store_dwordx4 v[98:99], v[90:93], off

; __device__ __forceinline__ unsigned cvt_pk(float lo, float hi) { unsigned r; asm volatile("v_cvt_pk_bf16_f32 %0, %1, %2" : "=v"(r) : "v"(lo), "v"(hi)); return r; }
;     __device__ __forceinline__ void operator()(const f32x4 (&acc)[2][2][4][2], const Unit& u, int wr, int wc, int fr, int fq) const {
;     ...
;         const int row0 = u.pm * BM + wr * 64 + fr, col0 = colt + wc * 32 + 8 * fq;
; #pragma unroll
;         for (int ai = 0; ai < 2; ++ai)
; #pragma unroll
;             for (int m = 0; m < 4; ++m) { const int row = row0 + ai * HALF + m * 16; const float rs = sc; bf16_t* rowp = base + (size_t)row * ldc + col0;
; #pragma unroll
;                 for (int bj = 0; bj < 2; ++bj) { const f32x4 v0 = acc[ai][bj][m][0] * rs, v1 = acc[ai][bj][m][1] * rs;
;                     u32x4 w; w.x = cvt_pk(v0[0], v0[1]); w.y = cvt_pk(v0[2], v0[3]); w.z = cvt_pk(v1[0], v1[1]); w.w = cvt_pk(v1[2], v1[3]);
;                     if (pn == 4 || pn == 5) *(u32x4*)((pn == 4 ? KB : VB) + ((size_t)bj * 40960 + row) * 128 + wc * 32 + 8 * fq) = w;
;                     else if (pn >= 18) __builtin_nontemporal_store(w, (u32x4*)(rowp + bj * HALF));
;                     else *(u32x4*)(rowp + bj * HALF) = w; } }
.LBB0_799:
	s_nop 1
	v_or_b32_e32 v84, 48, v156
	v_ashrrev_i32_e32 v85, 31, v84
	v_mov_b32_e32 v86, v152
	v_mov_b32_e32 v87, v152
	s_add_u32 s88, s88, s90
	s_addc_u32 s89, s89, s91
	v_lshl_add_u64 v[82:83], v[158:159], 0, s[88:89]
	v_pk_mul_f32 v[80:81], v[80:81], v[86:87]
	v_pk_mul_f32 v[86:87], v[76:77], v[86:87]
	v_pk_mul_f32 v[76:77], v[74:75], v[152:153]
	s_and_b64 vcc, exec, s[2:3]
	s_mov_b64 s[34:35], -1
	v_pk_mul_f32 v[78:79], v[78:79], v[152:153]
	s_nop 0
	v_cvt_pk_bf16_f32 v74, v78, v79
	v_cvt_pk_bf16_f32 v75, v80, v81
	v_cvt_pk_bf16_f32 v76, v76, v77
	v_cvt_pk_bf16_f32 v77, v86, v87
	s_cbranch_vccnz .LBB0_801
	s_mov_b64 s[34:35], 0
	global_store_dwordx4 v[82:83], v[74:77], off

; __device__ __forceinline__ unsigned cvt_pk(float lo, float hi) { unsigned r; asm volatile("v_cvt_pk_bf16_f32 %0, %1, %2" : "=v"(r) : "v"(lo), "v"(hi)); return r; }
;     __device__ __forceinline__ void operator()(const f32x4 (&acc)[2][2][4][2], const Unit& u, int wr, int wc, int fr, int fq) const {
;     ...
;         const int row0 = u.pm * BM + wr * 64 + fr, col0 = colt + wc * 32 + 8 * fq;
; #pragma unroll
;         for (int ai = 0; ai < 2; ++ai)
; #pragma unroll
;             for (int m = 0; m < 4; ++m) { const int row = row0 + ai * HALF + m * 16; const float rs = sc; bf16_t* rowp = base + (size_t)row * ldc + col0;
; #pragma unroll
;                 for (int bj = 0; bj < 2; ++bj) { const f32x4 v0 = acc[ai][bj][m][0] * rs, v1 = acc[ai][bj][m][1] * rs;
;                     u32x4 w; w.x = cvt_pk(v0[0], v0[1]); w.y = cvt_pk(v0[2], v0[3]); w.z = cvt_pk(v1[0], v1[1]); w.w = cvt_pk(v1[2], v1[3]);
;                     if (pn == 4 || pn == 5) *(u32x4*)((pn == 4 ? KB : VB) + ((size_t)bj * 40960 + row) * 128 + wc * 32 + 8 * fq) = w;
;                     else if (pn >= 18) __builtin_nontemporal_store(w, (u32x4*)(rowp + bj * HALF));
;                     else *(u32x4*)(rowp + bj * HALF) = w; } }
.LBB0_807:
	s_nop 1
	v_add_u32_e32 v68, 0x80, v156
	v_ashrrev_i32_e32 v69, 31, v68
	v_mov_b32_e32 v70, v152
	v_mov_b32_e32 v71, v152
	s_lshl_b64 s[88:89], s[90:91], 3
	v_lshl_add_u64 v[66:67], v[158:159], 0, s[88:89]
	v_pk_mul_f32 v[64:65], v[64:65], v[70:71]
	v_pk_mul_f32 v[70:71], v[60:61], v[70:71]
	v_pk_mul_f32 v[60:61], v[58:59], v[152:153]
	s_and_b64 vcc, exec, s[2:3]
	s_mov_b64 s[34:35], -1
	v_pk_mul_f32 v[62:63], v[62:63], v[152:153]
	s_nop 0
	v_cvt_pk_bf16_f32 v58, v62, v63
	v_cvt_pk_bf16_f32 v59, v64, v65
	v_cvt_pk_bf16_f32 v60, v60, v61
	v_cvt_pk_bf16_f32 v61, v70, v71
	s_cbranch_vccnz .LBB0_809
	s_mov_b64 s[34:35], 0
	global_store_dwordx4 v[66:67], v[58:61], off

; __device__ __forceinline__ unsigned cvt_pk(float lo, float hi) { unsigned r; asm volatile("v_cvt_pk_bf16_f32 %0, %1, %2" : "=v"(r) : "v"(lo), "v"(hi)); return r; }
;     __device__ __forceinline__ void operator()(const f32x4 (&acc)[2][2][4][2], const Unit& u, int wr, int wc, int fr, int fq) const {
;     ...
;         const int row0 = u.pm * BM + wr * 64 + fr, col0 = colt + wc * 32 + 8 * fq;
; #pragma unroll
;         for (int ai = 0; ai < 2; ++ai)
; #pragma unroll
;             for (int m = 0; m < 4; ++m) { const int row = row0 + ai * HALF + m * 16; const float rs = sc; bf16_t* rowp = base + (size_t)row * ldc + col0;
; #pragma unroll
;                 for (int bj = 0; bj < 2; ++bj) { const f32x4 v0 = acc[ai][bj][m][0] * rs, v1 = acc[ai][bj][m][1] * rs;
;                     u32x4 w; w.x = cvt_pk(v0[0], v0[1]); w.y = cvt_pk(v0[2], v0[3]); w.z = cvt_pk(v1[0], v1[1]); w.w = cvt_pk(v1[2], v1[3]);
;                     if (pn == 4 || pn == 5) *(u32x4*)((pn == 4 ? KB : VB) + ((size_t)bj * 40960 + row) * 128 + wc * 32 + 8 * fq) = w;
;                     else if (pn >= 18) __builtin_nontemporal_store(w, (u32x4*)(rowp + bj * HALF));
;                     else *(u32x4*)(rowp + bj * HALF) = w; } }
.LBB0_815:
	s_nop 1
	v_add_u32_e32 v52, 0x90, v156
	v_ashrrev_i32_e32 v53, 31, v52
	v_mov_b32_e32 v54, v152
	v_mov_b32_e32 v55, v152
	s_add_u32 s88, s88, s90
	s_addc_u32 s89, s89, s91
	v_lshl_add_u64 v[50:51], v[158:159], 0, s[88:89]
	v_pk_mul_f32 v[48:49], v[48:49], v[54:55]
	v_pk_mul_f32 v[54:55], v[44:45], v[54:55]
	v_pk_mul_f32 v[44:45], v[42:43], v[152:153]
	s_and_b64 vcc, exec, s[2:3]
	s_mov_b64 s[34:35], -1
	v_pk_mul_f32 v[46:47], v[46:47], v[152:153]
	s_nop 0
	v_cvt_pk_bf16_f32 v42, v46, v47
	v_cvt_pk_bf16_f32 v43, v48, v49
	v_cvt_pk_bf16_f32 v44, v44, v45
	v_cvt_pk_bf16_f32 v45, v54, v55
	s_cbranch_vccnz .LBB0_817
	s_mov_b64 s[34:35], 0
	global_store_dwordx4 v[50:51], v[42:45], off

; __device__ __forceinline__ unsigned cvt_pk(float lo, float hi) { unsigned r; asm volatile("v_cvt_pk_bf16_f32 %0, %1, %2" : "=v"(r) : "v"(lo), "v"(hi)); return r; }
;     __device__ __forceinline__ void operator()(const f32x4 (&acc)[2][2][4][2], const Unit& u, int wr, int wc, int fr, int fq) const {
;     ...
;         const int row0 = u.pm * BM + wr * 64 + fr, col0 = colt + wc * 32 + 8 * fq;
; #pragma unroll
;         for (int ai = 0; ai < 2; ++ai)
; #pragma unroll
;             for (int m = 0; m < 4; ++m) { const int row = row0 + ai * HALF + m * 16; const float rs = sc; bf16_t* rowp = base + (size_t)row * ldc + col0;
; #pragma unroll
;                 for (int bj = 0; bj < 2; ++bj) { const f32x4 v0 = acc[ai][bj][m][0] * rs, v1 = acc[ai][bj][m][1] * rs;
;                     u32x4 w; w.x = cvt_pk(v0[0], v0[1]); w.y = cvt_pk(v0[2], v0[3]); w.z = cvt_pk(v1[0], v1[1]); w.w = cvt_pk(v1[2], v1[3]);
;                     if (pn == 4 || pn == 5) *(u32x4*)((pn == 4 ? KB : VB) + ((size_t)bj * 40960 + row) * 128 + wc * 32 + 8 * fq) = w;
;                     else if (pn >= 18) __builtin_nontemporal_store(w, (u32x4*)(rowp + bj * HALF));
;                     else *(u32x4*)(rowp + bj * HALF) = w; } }
.LBB0_823:
	s_nop 1
	v_add_u32_e32 v36, 0xa0, v156
	v_ashrrev_i32_e32 v37, 31, v36
	v_mov_b32_e32 v38, v152
	v_mov_b32_e32 v39, v152
	s_add_u32 s88, s88, s90
	s_addc_u32 s89, s89, s91
	v_lshl_add_u64 v[34:35], v[158:159], 0, s[88:89]
	v_pk_mul_f32 v[32:33], v[32:33], v[38:39]
	v_pk_mul_f32 v[38:39], v[28:29], v[38:39]
	v_pk_mul_f32 v[28:29], v[26:27], v[152:153]
	s_and_b64 vcc, exec, s[2:3]
	s_mov_b64 s[34:35], -1
	v_pk_mul_f32 v[30:31], v[30:31], v[152:153]
	s_nop 0
	v_cvt_pk_bf16_f32 v26, v30, v31
	v_cvt_pk_bf16_f32 v27, v32, v33
	v_cvt_pk_bf16_f32 v28, v28, v29
	v_cvt_pk_bf16_f32 v29, v38, v39
	s_cbranch_vccnz .LBB0_825
	s_mov_b64 s[34:35], 0
	global_store_dwordx4 v[34:35], v[26:29], off

; __device__ __forceinline__ unsigned cvt_pk(float lo, float hi) { unsigned r; asm volatile("v_cvt_pk_bf16_f32 %0, %1, %2" : "=v"(r) : "v"(lo), "v"(hi)); return r; }
;     __device__ __forceinline__ void operator()(const f32x4 (&acc)[2][2][4][2], const Unit& u, int wr, int wc, int fr, int fq) const {
;     ...
;         const int row0 = u.pm * BM + wr * 64 + fr, col0 = colt + wc * 32 + 8 * fq;
; #pragma unroll
;         for (int ai = 0; ai < 2; ++ai)
; #pragma unroll
;             for (int m = 0; m < 4; ++m) { const int row = row0 + ai * HALF + m * 16; const float rs = sc; bf16_t* rowp = base + (size_t)row * ldc + col0;
; #pragma unroll
;                 for (int bj = 0; bj < 2; ++bj) { const f32x4 v0 = acc[ai][bj][m][0] * rs, v1 = acc[ai][bj][m][1] * rs;
;                     u32x4 w; w.x = cvt_pk(v0[0], v0[1]); w.y = cvt_pk(v0[2], v0[3]); w.z = cvt_pk(v1[0], v1[1]); w.w = cvt_pk(v1[2], v1[3]);
;                     if (pn == 4 || pn == 5) *(u32x4*)((pn == 4 ? KB : VB) + ((size_t)bj * 40960 + row) * 128 + wc * 32 + 8 * fq) = w;
;                     else if (pn >= 18) __builtin_nontemporal_store(w, (u32x4*)(rowp + bj * HALF));
;                     else *(u32x4*)(rowp + bj * HALF) = w; } }
.LBB0_831:
	s_nop 1
	v_add_u32_e32 v20, 0xb0, v156
	v_ashrrev_i32_e32 v21, 31, v20
	v_mov_b32_e32 v22, v152
	v_mov_b32_e32 v23, v152
	s_add_u32 s88, s88, s90
	s_addc_u32 s89, s89, s91
	v_lshl_add_u64 v[18:19], v[158:159], 0, s[88:89]
	v_pk_mul_f32 v[16:17], v[16:17], v[22:23]
	v_pk_mul_f32 v[22:23], v[12:13], v[22:23]
	v_pk_mul_f32 v[12:13], v[10:11], v[152:153]
	s_and_b64 vcc, exec, s[2:3]
	s_mov_b64 s[30:31], -1
	v_pk_mul_f32 v[14:15], v[14:15], v[152:153]
	s_nop 0
	v_cvt_pk_bf16_f32 v10, v14, v15
	v_cvt_pk_bf16_f32 v11, v16, v17
	v_cvt_pk_bf16_f32 v12, v12, v13
	v_cvt_pk_bf16_f32 v13, v22, v23
	s_cbranch_vccnz .LBB0_833
	s_mov_b64 s[30:31], 0
	global_store_dwordx4 v[18:19], v[10:13], off
